# v050 + rope-phase V transposes: 8 row loads issued together (were load-wait-store x8) + window-attention unit prologue: K/V and bias-table loads issued together (were 3 serialized round trips)
# baseline (speedup 1.0000x reference)
; #define LAS __attribute__((address_space(3)))
; #define INP(i) ldsptr(lds, (i))
; template <int HD, int MODE> ...
;     ...
;     int tid = tid_in; asm volatile("" : "+v"(tid));
;     const int lane = tid & 63, wid = __builtin_amdgcn_readfirstlane(tid >> 6), r32 = lane & 31, hi = lane >> 5;
;     bf16x8 qf[HD / 16];
;     { const gbf16* qrow = Qg + (size_t)(wid * 32 + r32) * q_pitch + hi * 8;
; #pragma unroll
;       for (int d0 = 0; d0 < HD / 16; ++d0) qf[d0] = *(const gbf16x8*)(qrow + d0 * 16); }
;     u32x4 kst[NP], vst[NP];
;     const gbf16* kg[NP]; const gbf16* vg[NP]; unsigned kl[NP], vl[NP];
; #pragma unroll
;     for (int p = 0; p < NP; ++p) { const int idx = tid + 512 * p; const int krow = idx / (HD / 8), kch = idx % (HD / 8), vd = idx >> 3, vch = idx & 7;
;         kg[p] = Kg + (size_t)krow * k_pitch + kch * 8; vg[p] = Vtg + (size_t)vd * vt_pitch + vch * 8;
;         kl[p] = krow * KROW + kch * 16; vl[p] = KBYTES + vd * VROW + vch * 16; }
;     ...
;     const int pr = (r32 & 0x13) | ((r32 & 4) << 1) | ((r32 & 8) >> 1);
;     const unsigned krd = pr * KROW + hi * 16, vrd = KBYTES + r32 * VROW + hi * 16;
;     f32x16 o[HD / 32];
; #pragma unroll
;     for (int d0 = 0; d0 < HD / 32; ++d0)
; #pragma unroll
;         for (int r = 0; r < 16; ++r) o[d0][r] = 0.f;
;     float m_run = m_init, l_run = l_init;
;     const LAS float* biasl = (const LAS float*)(lds + ATT_BIAS_OFF);
;     __syncthreads();
;     ATT_LOAD(t0); ATT_STORE(0);
; __global__ void __launch_bounds__(512, 2) mega_fwd(Args a) {
;     ...
;                 for (int u = vcu; ATT_EN(1) && u < (CH / 256) * 8; u += G) {
;                     const int qb = u % NQB, g4 = (u / NQB) % 4, kvh = (u / NQB / 4) % 2, seq = u / (NQB * 8), head = kvh * 4 + g4;
;                     const size_t tokq = (size_t)seq * S_ + (size_t)qb * 256;
;                     const int q0 = qb * 256;
;                     const int t0 = (q0 >= 128) ? (q0 - 128) / 64 : 0, t1 = min(S_, q0 + 384) / 64;
;                     attn_unit_np<64, 1>(lds, tid, proj + tokq * PROJ + 768 + 64 * head, PROJ, proj + (size_t)seq * S_ * PROJ + 1280 + 64 * kvh, PROJ,
;                                      vtb + ((size_t)(seq * 2 + kvh) * 64) * S_, S_, yb3 + (size_t)CH * 512 + tokq * 512 + 64 * head, 512, t0, t1,
;                                      0.125f * LOG2E, q0, biast + head * 768, INP(I_SINK)[head] * LOG2E, 1.0f);
.LBB0_514:
	s_abs_i32 s5, s45
	s_mul_hi_u32 s4, s5, s56
	s_mul_i32 s6, s4, s43
	s_ashr_i32 s2, s45, 31
	s_sub_i32 s6, s5, s6
	s_xor_b32 s3, s2, s42
	s_add_i32 s7, s4, 1
	s_sub_i32 s8, s6, s43
	s_cmp_ge_u32 s6, s43
	s_cselect_b32 s4, s7, s4
	s_cselect_b32 s6, s8, s6
	s_add_i32 s7, s4, 1
	s_cmp_ge_u32 s6, s43
	s_cselect_b32 s4, s7, s4
	s_xor_b32 s4, s4, s3
	s_sub_i32 s29, s4, s3
	s_mul_i32 s3, s29, s20
	s_sub_i32 s4, s45, s3
	s_ashr_i32 s3, s29, 31
	s_lshr_b32 s6, s3, 30
	s_add_i32 s6, s29, s6
	s_ashr_i32 s7, s6, 2
	s_lshr_b32 s6, s6, 31
	s_add_i32 s6, s7, s6
	s_and_b32 s6, s6, -2
	s_sub_i32 s7, s7, s6
	s_mul_hi_u32 s6, s5, s57
	s_mul_i32 s8, s6, s21
	s_sub_i32 s5, s5, s8
	s_add_i32 s8, s6, 1
	s_sub_i32 s9, s5, s21
	s_cmp_ge_u32 s5, s21
	s_cselect_b32 s6, s8, s6
	s_cselect_b32 s5, s9, s5
	s_add_i32 s8, s6, 1
	s_cmp_ge_u32 s5, s21
	s_cselect_b32 s5, s8, s6
	s_xor_b32 s5, s5, s2
	s_sub_i32 s10, s5, s2
	s_lshr_b32 s2, s3, 29
	s_add_i32 s2, s29, s2
	s_and_b32 s2, s2, -8
	s_ashr_i32 s11, s10, 31
	s_ashr_i32 s5, s4, 31
	s_sub_i32 s6, s29, s2
	s_lshl_b64 s[8:9], s[10:11], s41
	s_lshl_b64 s[2:3], s[4:5], 8
	s_add_u32 s2, s8, s2
	s_addc_u32 s3, s9, s3
	s_lshl_b32 s46, s4, 8
	s_add_i32 s5, s46, 0xffffff80
	s_lshr_b32 s5, s5, 6
	s_cmp_gt_i32 s4, 0
	s_cselect_b32 s31, s5, 0
	s_mul_i32 s4, s3, 0x2800
	s_mul_hi_u32 s5, s2, 0x2800
	s_add_i32 s5, s5, s4
	s_mul_i32 s4, s2, 0x2800
	s_add_u32 s11, s96, s4
	s_addc_u32 s16, s97, s5
	s_lshl_b32 s4, s6, 6
	s_ashr_i32 s5, s4, 31
	s_lshl_b64 s[4:5], s[4:5], 1
	s_add_u32 s50, s11, s4
	s_mulk_i32 s9, 0x2800
	s_mul_hi_u32 s11, s8, 0x2800
	s_addc_u32 s51, s16, s5
	s_add_i32 s47, s11, s9
	s_mul_i32 s48, s8, 0x2800
	s_add_u32 s11, s96, s48
	s_addc_u32 s17, s97, s47
	s_lshl_b32 s8, s7, 6
	s_ashr_i32 s9, s8, 31
	s_lshl_b64 s[8:9], s[8:9], 1
	s_add_u32 s16, s11, s8
	s_addc_u32 s17, s17, s9
	s_lshl_b32 s10, s10, 1
	s_add_i32 s10, s10, s7
	s_ashr_i32 s11, s10, 31
	s_lshl_b64 s[10:11], s[10:11], 6
	s_lshl_b64 s[10:11], s[10:11], s41
	s_lshl_b64 s[10:11], s[10:11], 1
	v_mov_b32_e32 v0, s61
	s_add_u32 s52, s36, s10
	s_mul_i32 s10, s6, 0x300
	ds_read_b64 v[2:3], v0
	s_addc_u32 s53, s37, s11
	s_ashr_i32 s11, s10, 31
	s_lshl_b64 s[10:11], s[10:11], 2
	s_add_u32 s10, s12, s10
	s_addc_u32 s11, s15, s11
	s_ashr_i32 s7, s6, 31
	s_waitcnt lgkmcnt(0)
	v_readfirstlane_b32 s39, v2
	s_lshl_b64 s[6:7], s[6:7], 2
	v_readfirstlane_b32 s30, v3
	s_add_u32 s6, s39, s6
	s_addc_u32 s7, s30, s7
	v_mov_b32_e32 v4, v240
	global_load_dword v8, v1, s[6:7]
	v_mov_b64_e32 v[2:3], s[50:51]
	v_readfirstlane_b32 s6, v4
	s_ashr_i32 s49, s6, 1
	v_mov_b32_e32 v0, s49
	v_bfe_u32 v98, v4, 5, 1
	v_bfi_b32 v90, s78, v0, v4
	v_mad_i64_i32 v[2:3], s[6:7], v90, s33, v[2:3]
	v_lshlrev_b32_e32 v0, 4, v98
	v_lshl_add_u64 v[2:3], v[2:3], 0, v[0:1]
	v_ashrrev_i32_e32 v5, 31, v4
	global_load_dwordx4 v[66:69], v[2:3], off offset:1536
	global_load_dwordx4 v[70:73], v[2:3], off offset:1568
	global_load_dwordx4 v[74:77], v[2:3], off offset:1600
	global_load_dwordx4 v[78:81], v[2:3], off offset:1632
	v_lshrrev_b32_e32 v2, 29, v5
	v_ashrrev_i32_e32 v6, 3, v4
	v_add_u32_e32 v2, v4, v2
	v_ashrrev_i32_e32 v7, 31, v6
	v_ashrrev_i32_e32 v9, 3, v2
	v_and_b32_e32 v2, -8, v2
	v_lshlrev_b64 v[10:11], s41, v[6:7]
	v_lshlrev_b32_e32 v7, 4, v4
	v_sub_u32_e32 v14, v4, v2
	v_lshl_add_u64 v[10:11], v[10:11], 1, s[52:53]
	v_and_b32_e32 v12, 0x70, v7
	v_mov_b32_e32 v13, v1
	v_lshlrev_b32_e32 v2, 3, v14
	v_lshl_add_u64 v[92:93], v[10:11], 0, v[12:13]
	v_mov_b64_e32 v[10:11], s[16:17]
	v_ashrrev_i32_e32 v3, 31, v2
	v_mad_i64_i32 v[10:11], s[6:7], v9, s33, v[10:11]
	v_lshl_add_u64 v[10:11], v[2:3], 1, v[10:11]
	s_mul_i32 s64, s31, 0x50000
	v_lshl_add_u64 v[10:11], s[64:65], 1, v[10:11]
	s_lshl_b32 s6, s31, 6
	s_mov_b32 s7, s65
	s_barrier
	global_load_dwordx4 v[82:85], v[10:11], off offset:2560
	v_lshl_add_u64 v[10:11], s[6:7], 1, v[92:93]
	global_load_dwordx4 v[86:89], v[10:11], off
	v_lshl_add_u64 v[128:129], v[4:5], 2, s[10:11]
	global_load_dword v130, v[128:129], off
	v_mul_lo_u32 v7, v9, s77
	v_lshl_add_u32 v91, v14, 4, v7
	v_mad_u64_u32 v[94:95], s[16:17], v6, s77, v[12:13]
	v_add_u32_e32 v7, 0, v91
	v_add_u32_e32 v6, 0, v94
	v_cmp_gt_i32_e32 vcc, s60, v4
	s_and_saveexec_b64 s[16:17], vcc
	s_cbranch_execz .Lb_pro_skip1
	global_load_dword v131, v[128:129], off offset:2048
.Lb_pro_skip1:
	s_or_b64 exec, exec, s[16:17]
	s_waitcnt vmcnt(0)
	ds_write_b128 v7, v[82:85]
	ds_write_b128 v6, v[86:89] offset:9216
	v_lshl_add_u32 v5, v4, 2, 0
	v_add_u32_e32 v5, 0x1b000, v5
	ds_write_b32 v5, v130
	s_and_saveexec_b64 s[10:11], vcc
	s_cbranch_execz .LBB0_516
	ds_write_b32 v5, v131 offset:2048

; #define LAS __attribute__((address_space(3)))
; __device__ __forceinline__ void transpose64_bf16(const gbf16* src, size_t src_pitch, gbf16* dst, size_t dst_pitch, LAS unsigned short* scr, int lane) {
; #pragma unroll
;     for (int p = 0; p < 8; ++p) { const int row = 8 * p + (lane >> 3), ch = lane & 7; const u32x4 v = *(const gu32x4*)(src + (size_t)row * src_pitch + 8 * ch);
;         LAS unsigned short* d = scr + row * 66 + 8 * ch;
;         d[0] = (unsigned short)v.x; d[1] = (unsigned short)(v.x >> 16); d[2] = (unsigned short)v.y; d[3] = (unsigned short)(v.y >> 16);
;         d[4] = (unsigned short)v.z; d[5] = (unsigned short)(v.z >> 16); d[6] = (unsigned short)v.w; d[7] = (unsigned short)(v.w >> 16); }
;     asm volatile("s_waitcnt lgkmcnt(0)" ::: "memory");
; __global__ void __launch_bounds__(512, 2) mega_fwd(Args a) {
;     ...
;                 for (int it = gw; it < (CH / 64) * 4; it += NGW) {
;                     const int kvh = it & 1, which = (it >> 1) & 1, tt = it >> 2;
;                     const int tok = 64 * tt, seq = tok / S_, pos = tok % S_;
;                     transpose64_bf16(proj + (size_t)tok * PROJ + (which ? 1408 : 640) + 64 * kvh, PROJ,
;                                      (which ? vtb : vta) + ((size_t)(seq * 2 + kvh) * 64) * S_ + pos, S_, scr, lane);
;                 }
.LBB0_547:
	s_and_b32 s1, s7, 0xffffffc0
	s_ashr_i32 s0, s7, 31
	s_add_i32 s15, s1, s0
	s_xor_b32 s12, s0, s5
	s_xor_b32 s0, s15, s0
	s_mul_hi_u32 s15, s0, s6
	s_mul_i32 s16, s15, s3
	s_sub_i32 s0, s0, s16
	s_add_i32 s16, s15, 1
	s_sub_i32 s17, s0, s3
	s_cmp_ge_u32 s0, s3
	s_cselect_b32 s15, s16, s15
	s_cselect_b32 s0, s17, s0
	s_add_i32 s16, s15, 1
	s_cmp_ge_u32 s0, s3
	s_cselect_b32 s0, s16, s15
	s_xor_b32 s0, s0, s12
	s_sub_i32 s12, s0, s12
	s_mul_i32 s0, s12, s38
	s_sub_i32 s0, s1, s0
	s_mul_hi_i32 s15, s1, 0x2800
	s_mulk_i32 s1, 0x2800
	s_add_u32 s1, s96, s1
	s_addc_u32 s15, s97, s15
	s_bitcmp0_b32 s9, 1
	s_movk_i32 s16, 0x500
	s_cselect_b32 s16, s16, 0xb00
	s_cselect_b32 s23, s35, s37
	s_cselect_b32 s24, s34, s36
	s_add_u32 s1, s1, s16
	s_addc_u32 s15, s15, 0
	s_add_u32 s16, s1, s8
	s_addc_u32 s17, s15, 0
	v_lshl_add_u64 v[34:35], s[16:17], 0, v[0:1]
	v_lshl_add_u64 v[38:39], v[34:35], 0, v[2:3]
	global_load_dwordx4 v[44:47], v[38:39], off
	v_lshl_add_u64 v[38:39], v[34:35], 0, v[4:5]
	global_load_dwordx4 v[48:51], v[38:39], off
	v_lshl_add_u64 v[38:39], v[34:35], 0, v[8:9]
	global_load_dwordx4 v[52:55], v[38:39], off
	v_lshl_add_u64 v[38:39], v[34:35], 0, v[10:11]
	global_load_dwordx4 v[56:59], v[38:39], off
	v_lshl_add_u64 v[38:39], v[34:35], 0, v[12:13]
	global_load_dwordx4 v[60:63], v[38:39], off
	v_lshl_add_u64 v[38:39], v[34:35], 0, v[14:15]
	global_load_dwordx4 v[64:67], v[38:39], off
	v_lshl_add_u64 v[38:39], v[34:35], 0, v[16:17]
	global_load_dwordx4 v[68:71], v[38:39], off
	v_lshl_add_u64 v[38:39], v[34:35], 0, v[18:19]
	global_load_dwordx4 v[72:75], v[38:39], off
	v_add_u32_e32 v7, 0x420, v37
	s_lshl_b32 s1, s12, 1
	s_or_b32 s20, s1, s4
	s_ashr_i32 s21, s20, 31
	s_lshl_b64 s[20:21], s[20:21], 6
	s_lshl_b64 s[20:21], s[20:21], s2
	s_lshl_b64 s[20:21], s[20:21], 1
	s_add_u32 s12, s24, s20
	s_addc_u32 s15, s23, s21
	s_ashr_i32 s1, s0, 31
	s_lshl_b64 s[0:1], s[0:1], 1
	s_add_u32 s0, s12, s0
	s_addc_u32 s1, s15, s1
	v_mov_b32_e32 v25, v1
	v_mov_b32_e32 v27, v1
	v_mov_b32_e32 v29, v1
	v_mov_b32_e32 v31, v1
	v_mov_b32_e32 v33, v1
	s_add_i32 s9, s9, s18
	s_add_i32 s7, s7, s19
	s_cmpk_gt_i32 s9, 0x7ff
	v_lshl_add_u64 v[34:35], s[0:1], 0, v[0:1]
	s_waitcnt vmcnt(7)
	ds_write2_b32 v37, v44, v45 offset1:1
	ds_write2_b32 v37, v46, v47 offset0:2 offset1:3
	s_waitcnt vmcnt(6)
	v_add_u32_e32 v7, 0x420, v37
	ds_write2_b32 v7, v48, v49 offset1:1
	v_add_u32_e32 v7, 0x428, v37
	ds_write2_b32 v7, v50, v51 offset1:1
	s_waitcnt vmcnt(5)
	v_add_u32_e32 v7, 0x840, v37
	ds_write2_b32 v7, v52, v53 offset1:1
	v_add_u32_e32 v7, 0x848, v37
	ds_write2_b32 v7, v54, v55 offset1:1
	s_waitcnt vmcnt(4)
	v_add_u32_e32 v7, 0xc60, v37
	ds_write2_b32 v7, v56, v57 offset1:1
	v_add_u32_e32 v7, 0xc68, v37
	ds_write2_b32 v7, v58, v59 offset1:1
	s_waitcnt vmcnt(3)
	v_add_u32_e32 v7, 0x1080, v37
	ds_write2_b32 v7, v60, v61 offset1:1
	v_add_u32_e32 v7, 0x1088, v37
	ds_write2_b32 v7, v62, v63 offset1:1
	s_waitcnt vmcnt(2)
	v_add_u32_e32 v7, 0x14a0, v37
	ds_write2_b32 v7, v64, v65 offset1:1
	v_add_u32_e32 v7, 0x14a8, v37
	ds_write2_b32 v7, v66, v67 offset1:1
	s_waitcnt vmcnt(1)
	v_add_u32_e32 v7, 0x18c0, v37
	ds_write2_b32 v7, v68, v69 offset1:1
	v_add_u32_e32 v7, 0x18c8, v37
	ds_write2_b32 v7, v70, v71 offset1:1
	s_waitcnt vmcnt(0)
	v_add_u32_e32 v7, 0x1ce0, v37
	ds_write2_b32 v7, v72, v73 offset1:1
	v_add_u32_e32 v7, 0x1ce8, v37
	ds_write2_b32 v7, v74, v75 offset1:1
	s_waitcnt lgkmcnt(0)
	ds_read_u16 v7, v36 offset:132
	ds_read_u16 v21, v36
	ds_read_u16 v23, v36 offset:16
	s_waitcnt lgkmcnt(1)
	v_lshl_or_b32 v38, v7, 16, v21
	ds_read_u16 v7, v36 offset:264
	ds_read_u16 v21, v36 offset:396
	s_waitcnt lgkmcnt(0)
	v_lshl_or_b32 v39, v21, 16, v7
	ds_read_u16 v7, v36 offset:528
	ds_read_u16 v21, v36 offset:660
	s_waitcnt lgkmcnt(0)
	v_lshl_or_b32 v40, v21, 16, v7
	ds_read_u16 v7, v36 offset:792
	ds_read_u16 v21, v36 offset:924
	s_waitcnt lgkmcnt(0)
	v_lshl_or_b32 v41, v21, 16, v7
	v_mov_b32_e32 v7, v1
	v_lshl_add_u64 v[42:43], v[34:35], 0, v[6:7]
	ds_read_u16 v7, v36 offset:148
	global_store_dwordx4 v[42:43], v[38:41], off
	s_waitcnt lgkmcnt(0)
; #define LAS __attribute__((address_space(3)))
; __device__ __forceinline__ void transpose64_bf16(const gbf16* src, size_t src_pitch, gbf16* dst, size_t dst_pitch, LAS unsigned short* scr, int lane) {
;     ...
; #pragma unroll
;     for (int p = 0; p < 8; ++p) { const int j = 8 * p + (lane >> 3), i0 = 8 * (lane & 7); const LAS unsigned short* s = scr + i0 * 66 + j;
;         u32x4 o; o.x = (unsigned)s[0] | ((unsigned)s[66] << 16); o.y = (unsigned)s[2 * 66] | ((unsigned)s[3 * 66] << 16);
;         o.z = (unsigned)s[4 * 66] | ((unsigned)s[5 * 66] << 16); o.w = (unsigned)s[6 * 66] | ((unsigned)s[7 * 66] << 16);
;         *(gu32x4*)(dst + (size_t)j * dst_pitch + i0) = o; }
;     asm volatile("s_waitcnt lgkmcnt(0)" ::: "memory");
	s_nop 0
	v_lshl_or_b32 v38, v7, 16, v23
	ds_read_u16 v7, v36 offset:280
	ds_read_u16 v21, v36 offset:412
	v_mov_b32_e32 v23, v1
	s_waitcnt lgkmcnt(0)
	v_lshl_or_b32 v39, v21, 16, v7
	ds_read_u16 v7, v36 offset:544
	ds_read_u16 v21, v36 offset:676
	s_waitcnt lgkmcnt(0)
	v_lshl_or_b32 v40, v21, 16, v7
	ds_read_u16 v7, v36 offset:808
	ds_read_u16 v21, v36 offset:940
	s_waitcnt lgkmcnt(0)
	v_lshl_or_b32 v41, v21, 16, v7
	v_mov_b32_e32 v21, v1
	v_lshl_add_u64 v[42:43], v[34:35], 0, v[20:21]
	global_store_dwordx4 v[42:43], v[38:41], off
	ds_read_u16 v7, v36 offset:32
	ds_read_u16 v21, v36 offset:164
	v_lshl_add_u64 v[42:43], v[34:35], 0, v[22:23]
	s_waitcnt lgkmcnt(0)
	v_lshl_or_b32 v38, v21, 16, v7
	ds_read_u16 v7, v36 offset:296
	ds_read_u16 v21, v36 offset:428
	s_waitcnt lgkmcnt(0)
	v_lshl_or_b32 v39, v21, 16, v7
	ds_read_u16 v7, v36 offset:560
	ds_read_u16 v21, v36 offset:692
	s_waitcnt lgkmcnt(0)
	v_lshl_or_b32 v40, v21, 16, v7
	ds_read_u16 v7, v36 offset:824
	ds_read_u16 v21, v36 offset:956
	s_waitcnt lgkmcnt(0)
	v_lshl_or_b32 v41, v21, 16, v7
	global_store_dwordx4 v[42:43], v[38:41], off
	ds_read_u16 v7, v36 offset:48
	ds_read_u16 v21, v36 offset:180
	v_lshl_add_u64 v[42:43], v[34:35], 0, v[24:25]
	s_waitcnt lgkmcnt(0)
	v_lshl_or_b32 v38, v21, 16, v7
	ds_read_u16 v7, v36 offset:312
	ds_read_u16 v21, v36 offset:444
	s_waitcnt lgkmcnt(0)
	v_lshl_or_b32 v39, v21, 16, v7
	ds_read_u16 v7, v36 offset:576
	ds_read_u16 v21, v36 offset:708
	s_waitcnt lgkmcnt(0)
	v_lshl_or_b32 v40, v21, 16, v7
	ds_read_u16 v7, v36 offset:840
	ds_read_u16 v21, v36 offset:972
	s_waitcnt lgkmcnt(0)
	v_lshl_or_b32 v41, v21, 16, v7
	global_store_dwordx4 v[42:43], v[38:41], off
	ds_read_u16 v7, v36 offset:64
	ds_read_u16 v21, v36 offset:196
	v_lshl_add_u64 v[42:43], v[34:35], 0, v[26:27]
	s_waitcnt lgkmcnt(0)
	v_lshl_or_b32 v38, v21, 16, v7
	ds_read_u16 v7, v36 offset:328
	ds_read_u16 v21, v36 offset:460
	s_waitcnt lgkmcnt(0)
	v_lshl_or_b32 v39, v21, 16, v7
	ds_read_u16 v7, v36 offset:592
	ds_read_u16 v21, v36 offset:724
	s_waitcnt lgkmcnt(0)
	v_lshl_or_b32 v40, v21, 16, v7
	ds_read_u16 v7, v36 offset:856
	ds_read_u16 v21, v36 offset:988
	s_waitcnt lgkmcnt(0)
	v_lshl_or_b32 v41, v21, 16, v7
	global_store_dwordx4 v[42:43], v[38:41], off
	ds_read_u16 v7, v36 offset:80
	ds_read_u16 v21, v36 offset:212
	v_lshl_add_u64 v[42:43], v[34:35], 0, v[28:29]
	s_waitcnt lgkmcnt(0)
	v_lshl_or_b32 v38, v21, 16, v7
	ds_read_u16 v7, v36 offset:344
	ds_read_u16 v21, v36 offset:476
	s_waitcnt lgkmcnt(0)
	v_lshl_or_b32 v39, v21, 16, v7
	ds_read_u16 v7, v36 offset:608
	ds_read_u16 v21, v36 offset:740
	s_waitcnt lgkmcnt(0)
	v_lshl_or_b32 v40, v21, 16, v7
	ds_read_u16 v7, v36 offset:872
	ds_read_u16 v21, v36 offset:1004
	s_waitcnt lgkmcnt(0)
	v_lshl_or_b32 v41, v21, 16, v7
	global_store_dwordx4 v[42:43], v[38:41], off
	ds_read_u16 v7, v36 offset:96
	ds_read_u16 v21, v36 offset:228
	v_lshl_add_u64 v[42:43], v[34:35], 0, v[30:31]
	v_lshl_add_u64 v[34:35], v[34:35], 0, v[32:33]
	s_waitcnt lgkmcnt(0)
	v_lshl_or_b32 v38, v21, 16, v7
	ds_read_u16 v7, v36 offset:360
	ds_read_u16 v21, v36 offset:492
	s_waitcnt lgkmcnt(0)
	v_lshl_or_b32 v39, v21, 16, v7
	ds_read_u16 v7, v36 offset:624
	ds_read_u16 v21, v36 offset:756
	s_waitcnt lgkmcnt(0)
	v_lshl_or_b32 v40, v21, 16, v7
	ds_read_u16 v7, v36 offset:888
	ds_read_u16 v21, v36 offset:1020
	s_waitcnt lgkmcnt(0)
	v_lshl_or_b32 v41, v21, 16, v7
	global_store_dwordx4 v[42:43], v[38:41], off
	ds_read_u16 v7, v36 offset:112
	ds_read_u16 v21, v36 offset:244
	s_waitcnt lgkmcnt(0)
	v_lshl_or_b32 v38, v21, 16, v7
	ds_read_u16 v7, v36 offset:376
	ds_read_u16 v21, v36 offset:508
	s_waitcnt lgkmcnt(0)
	v_lshl_or_b32 v39, v21, 16, v7
	ds_read_u16 v7, v36 offset:640
	ds_read_u16 v21, v36 offset:772
	s_waitcnt lgkmcnt(0)
	v_lshl_or_b32 v40, v21, 16, v7
	ds_read_u16 v7, v36 offset:904
	ds_read_u16 v21, v36 offset:1036
	s_waitcnt lgkmcnt(0)
	v_lshl_or_b32 v41, v21, 16, v7
	global_store_dwordx4 v[34:35], v[38:41], off
	s_waitcnt lgkmcnt(0)
	s_cbranch_scc0 .LBB0_547
